# FFN-up / projection: previous tile's stores retire (s_waitcnt vmcnt(0)) after the accumulator clears, right before the main loop
# baseline (speedup 1.0000x reference)
.LBB0_233:
	s_ashr_i32 s15, s14, 31
	s_lshl_b64 s[16:17], s[14:15], 19
	s_add_u32 s16, s26, s16
	s_addc_u32 s17, s27, s17
	s_and_b64 s[18:19], s[4:5], exec
	s_cselect_b32 s15, s17, s21
	s_cselect_b32 s42, s16, s20
	s_ashr_i32 s13, s12, 31
	s_lshl_b64 s[18:19], s[12:13], 19
	s_add_u32 s18, s28, s18
	s_addc_u32 s19, s29, s19
	s_and_b64 s[24:25], s[4:5], exec
	s_cselect_b32 s13, s19, s23
	s_cselect_b32 s43, s18, s22
	s_add_u32 s20, s20, 0x40080
	s_addc_u32 s21, s21, 0
	s_add_u32 s44, s22, 0x100
	v_mov_b32_e32 v2, 0
	s_addc_u32 s45, s23, 0
	s_mov_b32 s46, -2
	v_mov_b32_e32 v3, v2
	v_mov_b32_e32 v4, v2
	v_mov_b32_e32 v5, v2
	v_mov_b32_e32 v6, v2
	v_mov_b32_e32 v7, v2
	v_mov_b32_e32 v8, v2
	v_mov_b32_e32 v9, v2
	v_mov_b32_e32 v18, v2
	v_mov_b32_e32 v19, v2
	v_mov_b32_e32 v20, v2
	v_mov_b32_e32 v21, v2
	v_mov_b32_e32 v22, v2
	v_mov_b32_e32 v23, v2
	v_mov_b32_e32 v24, v2
	v_mov_b32_e32 v25, v2
	v_mov_b32_e32 v34, v2
	v_mov_b32_e32 v35, v2
	v_mov_b32_e32 v36, v2
	v_mov_b32_e32 v37, v2
	v_mov_b32_e32 v38, v2
	v_mov_b32_e32 v39, v2
	v_mov_b32_e32 v40, v2
	v_mov_b32_e32 v41, v2
	v_mov_b32_e32 v50, v2
	v_mov_b32_e32 v51, v2
	v_mov_b32_e32 v52, v2
	v_mov_b32_e32 v53, v2
	v_mov_b32_e32 v54, v2
	v_mov_b32_e32 v55, v2
	v_mov_b32_e32 v56, v2
	v_mov_b32_e32 v57, v2
	v_mov_b32_e32 v10, v2
	v_mov_b32_e32 v11, v2
	v_mov_b32_e32 v12, v2
	v_mov_b32_e32 v13, v2
	v_mov_b32_e32 v14, v2
	v_mov_b32_e32 v15, v2
	v_mov_b32_e32 v16, v2
	v_mov_b32_e32 v17, v2
	v_mov_b32_e32 v26, v2
	v_mov_b32_e32 v27, v2
	v_mov_b32_e32 v28, v2
	v_mov_b32_e32 v29, v2
	v_mov_b32_e32 v30, v2
	v_mov_b32_e32 v31, v2
	v_mov_b32_e32 v32, v2
	v_mov_b32_e32 v33, v2
	v_mov_b32_e32 v42, v2
	v_mov_b32_e32 v43, v2
	v_mov_b32_e32 v44, v2
	v_mov_b32_e32 v45, v2
	v_mov_b32_e32 v46, v2
	v_mov_b32_e32 v47, v2
	v_mov_b32_e32 v48, v2
	v_mov_b32_e32 v49, v2
	v_mov_b32_e32 v58, v2
	v_mov_b32_e32 v59, v2
	v_mov_b32_e32 v60, v2
	v_mov_b32_e32 v61, v2
	v_mov_b32_e32 v62, v2
	v_mov_b32_e32 v63, v2
	v_mov_b32_e32 v64, v2
	v_mov_b32_e32 v65, v2
	v_mov_b32_e32 v66, v2
	v_mov_b32_e32 v67, v2
	v_mov_b32_e32 v68, v2
	v_mov_b32_e32 v69, v2
	v_mov_b32_e32 v70, v2
	v_mov_b32_e32 v71, v2
	v_mov_b32_e32 v72, v2
	v_mov_b32_e32 v73, v2
	v_mov_b32_e32 v82, v2
	v_mov_b32_e32 v83, v2
	v_mov_b32_e32 v84, v2
	v_mov_b32_e32 v85, v2
	v_mov_b32_e32 v86, v2
	v_mov_b32_e32 v87, v2
	v_mov_b32_e32 v88, v2
	v_mov_b32_e32 v89, v2
	v_mov_b32_e32 v98, v2
	v_mov_b32_e32 v99, v2
	v_mov_b32_e32 v100, v2
	v_mov_b32_e32 v101, v2
	v_mov_b32_e32 v102, v2
	v_mov_b32_e32 v103, v2
	v_mov_b32_e32 v104, v2
	v_mov_b32_e32 v105, v2
	v_mov_b32_e32 v114, v2
	v_mov_b32_e32 v115, v2
	v_mov_b32_e32 v116, v2
	v_mov_b32_e32 v117, v2
	v_mov_b32_e32 v118, v2
	v_mov_b32_e32 v119, v2
	v_mov_b32_e32 v120, v2
	v_mov_b32_e32 v121, v2
	v_mov_b32_e32 v74, v2
	v_mov_b32_e32 v75, v2
	v_mov_b32_e32 v76, v2
	v_mov_b32_e32 v77, v2
	v_mov_b32_e32 v78, v2
	v_mov_b32_e32 v79, v2
	v_mov_b32_e32 v80, v2
	v_mov_b32_e32 v81, v2
	v_mov_b32_e32 v90, v2
	v_mov_b32_e32 v91, v2
	v_mov_b32_e32 v92, v2
	v_mov_b32_e32 v93, v2
	v_mov_b32_e32 v94, v2
	v_mov_b32_e32 v95, v2
	v_mov_b32_e32 v96, v2
	v_mov_b32_e32 v97, v2
	v_mov_b32_e32 v106, v2
	v_mov_b32_e32 v107, v2
	v_mov_b32_e32 v108, v2
	v_mov_b32_e32 v109, v2
	v_mov_b32_e32 v110, v2
	v_mov_b32_e32 v111, v2
	v_mov_b32_e32 v112, v2
	v_mov_b32_e32 v113, v2
	v_mov_b32_e32 v122, v2
	v_mov_b32_e32 v123, v2
	v_mov_b32_e32 v124, v2
	v_mov_b32_e32 v125, v2
	v_mov_b32_e32 v126, v2
	v_mov_b32_e32 v127, v2
	v_mov_b32_e32 v128, v2
	v_mov_b32_e32 v129, v2
	s_waitcnt vmcnt(0)

.LBB0_393:
	s_ashr_i32 s17, s16, 31
	s_lshl_b64 s[18:19], s[16:17], 19
	s_add_u32 s18, s26, s18
	s_addc_u32 s19, s27, s19
	s_and_b64 s[20:21], s[8:9], exec
	s_cselect_b32 s17, s19, s11
	s_cselect_b32 s42, s18, s10
	s_ashr_i32 s15, s14, 31
	s_lshl_b64 s[20:21], s[14:15], 19
	s_add_u32 s20, s28, s20
	s_addc_u32 s21, s29, s21
	s_and_b64 s[24:25], s[8:9], exec
	s_cselect_b32 s15, s21, s23
	s_cselect_b32 s43, s20, s22
	s_add_u32 s10, s10, 0x40080
	s_addc_u32 s11, s11, 0
	s_add_u32 s44, s22, 0x100
	v_mov_b32_e32 v2, 0
	s_addc_u32 s45, s23, 0
	s_mov_b32 s46, -2
	v_mov_b32_e32 v3, v2
	v_mov_b32_e32 v4, v2
	v_mov_b32_e32 v5, v2
	v_mov_b32_e32 v6, v2
	v_mov_b32_e32 v7, v2
	v_mov_b32_e32 v8, v2
	v_mov_b32_e32 v9, v2
	v_mov_b32_e32 v18, v2
	v_mov_b32_e32 v19, v2
	v_mov_b32_e32 v20, v2
	v_mov_b32_e32 v21, v2
	v_mov_b32_e32 v22, v2
	v_mov_b32_e32 v23, v2
	v_mov_b32_e32 v24, v2
	v_mov_b32_e32 v25, v2
	v_mov_b32_e32 v34, v2
	v_mov_b32_e32 v35, v2
	v_mov_b32_e32 v36, v2
	v_mov_b32_e32 v37, v2
	v_mov_b32_e32 v38, v2
	v_mov_b32_e32 v39, v2
	v_mov_b32_e32 v40, v2
	v_mov_b32_e32 v41, v2
	v_mov_b32_e32 v50, v2
	v_mov_b32_e32 v51, v2
	v_mov_b32_e32 v52, v2
	v_mov_b32_e32 v53, v2
	v_mov_b32_e32 v54, v2
	v_mov_b32_e32 v55, v2
	v_mov_b32_e32 v56, v2
	v_mov_b32_e32 v57, v2
	v_mov_b32_e32 v10, v2
	v_mov_b32_e32 v11, v2
	v_mov_b32_e32 v12, v2
	v_mov_b32_e32 v13, v2
	v_mov_b32_e32 v14, v2
	v_mov_b32_e32 v15, v2
	v_mov_b32_e32 v16, v2
	v_mov_b32_e32 v17, v2
	v_mov_b32_e32 v26, v2
	v_mov_b32_e32 v27, v2
	v_mov_b32_e32 v28, v2
	v_mov_b32_e32 v29, v2
	v_mov_b32_e32 v30, v2
	v_mov_b32_e32 v31, v2
	v_mov_b32_e32 v32, v2
	v_mov_b32_e32 v33, v2
	v_mov_b32_e32 v42, v2
	v_mov_b32_e32 v43, v2
	v_mov_b32_e32 v44, v2
	v_mov_b32_e32 v45, v2
	v_mov_b32_e32 v46, v2
	v_mov_b32_e32 v47, v2
	v_mov_b32_e32 v48, v2
	v_mov_b32_e32 v49, v2
	v_mov_b32_e32 v58, v2
	v_mov_b32_e32 v59, v2
	v_mov_b32_e32 v60, v2
	v_mov_b32_e32 v61, v2
	v_mov_b32_e32 v62, v2
	v_mov_b32_e32 v63, v2
	v_mov_b32_e32 v64, v2
	v_mov_b32_e32 v65, v2
	v_mov_b32_e32 v66, v2
	v_mov_b32_e32 v67, v2
	v_mov_b32_e32 v68, v2
	v_mov_b32_e32 v69, v2
	v_mov_b32_e32 v70, v2
	v_mov_b32_e32 v71, v2
	v_mov_b32_e32 v72, v2
	v_mov_b32_e32 v73, v2
	v_mov_b32_e32 v82, v2
	v_mov_b32_e32 v83, v2
	v_mov_b32_e32 v84, v2
	v_mov_b32_e32 v85, v2
	v_mov_b32_e32 v86, v2
	v_mov_b32_e32 v87, v2
	v_mov_b32_e32 v88, v2
	v_mov_b32_e32 v89, v2
	v_mov_b32_e32 v98, v2
	v_mov_b32_e32 v99, v2
	v_mov_b32_e32 v100, v2
	v_mov_b32_e32 v101, v2
	v_mov_b32_e32 v102, v2
	v_mov_b32_e32 v103, v2
	v_mov_b32_e32 v104, v2
	v_mov_b32_e32 v105, v2
	v_mov_b32_e32 v114, v2
	v_mov_b32_e32 v115, v2
	v_mov_b32_e32 v116, v2
	v_mov_b32_e32 v117, v2
	v_mov_b32_e32 v118, v2
	v_mov_b32_e32 v119, v2
	v_mov_b32_e32 v120, v2
	v_mov_b32_e32 v121, v2
	v_mov_b32_e32 v74, v2
	v_mov_b32_e32 v75, v2
	v_mov_b32_e32 v76, v2
	v_mov_b32_e32 v77, v2
	v_mov_b32_e32 v78, v2
	v_mov_b32_e32 v79, v2
	v_mov_b32_e32 v80, v2
	v_mov_b32_e32 v81, v2
	v_mov_b32_e32 v90, v2
	v_mov_b32_e32 v91, v2
	v_mov_b32_e32 v92, v2
	v_mov_b32_e32 v93, v2
	v_mov_b32_e32 v94, v2
	v_mov_b32_e32 v95, v2
	v_mov_b32_e32 v96, v2
	v_mov_b32_e32 v97, v2
	v_mov_b32_e32 v106, v2
	v_mov_b32_e32 v107, v2
	v_mov_b32_e32 v108, v2
	v_mov_b32_e32 v109, v2
	v_mov_b32_e32 v110, v2
	v_mov_b32_e32 v111, v2
	v_mov_b32_e32 v112, v2
	v_mov_b32_e32 v113, v2
	v_mov_b32_e32 v122, v2
	v_mov_b32_e32 v123, v2
	v_mov_b32_e32 v124, v2
	v_mov_b32_e32 v125, v2
	v_mov_b32_e32 v126, v2
	v_mov_b32_e32 v127, v2
	v_mov_b32_e32 v128, v2
	v_mov_b32_e32 v129, v2
	s_waitcnt vmcnt(0)

.LBB0_1601:
	s_ashr_i32 s15, s14, 31
	s_lshl_b64 s[16:17], s[14:15], 19
	s_add_u32 s16, s26, s16
	s_addc_u32 s17, s27, s17
	s_and_b64 s[18:19], s[6:7], exec
	s_cselect_b32 s15, s17, s21
	s_cselect_b32 s42, s16, s20
	s_ashr_i32 s13, s12, 31
	s_lshl_b64 s[18:19], s[12:13], 19
	s_add_u32 s18, s28, s18
	s_addc_u32 s19, s29, s19
	s_and_b64 s[24:25], s[6:7], exec
	s_cselect_b32 s13, s19, s23
	s_cselect_b32 s43, s18, s22
	s_add_u32 s20, s20, 0x40080
	s_addc_u32 s21, s21, 0
	s_add_u32 s44, s22, 0x100
	v_mov_b32_e32 v2, 0
	s_addc_u32 s45, s23, 0
	s_mov_b32 s46, -2
	v_mov_b32_e32 v3, v2
	v_mov_b32_e32 v4, v2
	v_mov_b32_e32 v5, v2
	v_mov_b32_e32 v6, v2
	v_mov_b32_e32 v7, v2
	v_mov_b32_e32 v8, v2
	v_mov_b32_e32 v9, v2
	v_mov_b32_e32 v18, v2
	v_mov_b32_e32 v19, v2
	v_mov_b32_e32 v20, v2
	v_mov_b32_e32 v21, v2
	v_mov_b32_e32 v22, v2
	v_mov_b32_e32 v23, v2
	v_mov_b32_e32 v24, v2
	v_mov_b32_e32 v25, v2
	v_mov_b32_e32 v34, v2
	v_mov_b32_e32 v35, v2
	v_mov_b32_e32 v36, v2
	v_mov_b32_e32 v37, v2
	v_mov_b32_e32 v38, v2
	v_mov_b32_e32 v39, v2
	v_mov_b32_e32 v40, v2
	v_mov_b32_e32 v41, v2
	v_mov_b32_e32 v50, v2
	v_mov_b32_e32 v51, v2
	v_mov_b32_e32 v52, v2
	v_mov_b32_e32 v53, v2
	v_mov_b32_e32 v54, v2
	v_mov_b32_e32 v55, v2
	v_mov_b32_e32 v56, v2
	v_mov_b32_e32 v57, v2
	v_mov_b32_e32 v10, v2
	v_mov_b32_e32 v11, v2
	v_mov_b32_e32 v12, v2
	v_mov_b32_e32 v13, v2
	v_mov_b32_e32 v14, v2
	v_mov_b32_e32 v15, v2
	v_mov_b32_e32 v16, v2
	v_mov_b32_e32 v17, v2
	v_mov_b32_e32 v26, v2
	v_mov_b32_e32 v27, v2
	v_mov_b32_e32 v28, v2
	v_mov_b32_e32 v29, v2
	v_mov_b32_e32 v30, v2
	v_mov_b32_e32 v31, v2
	v_mov_b32_e32 v32, v2
	v_mov_b32_e32 v33, v2
	v_mov_b32_e32 v42, v2
	v_mov_b32_e32 v43, v2
	v_mov_b32_e32 v44, v2
	v_mov_b32_e32 v45, v2
	v_mov_b32_e32 v46, v2
	v_mov_b32_e32 v47, v2
	v_mov_b32_e32 v48, v2
	v_mov_b32_e32 v49, v2
	v_mov_b32_e32 v58, v2
	v_mov_b32_e32 v59, v2
	v_mov_b32_e32 v60, v2
	v_mov_b32_e32 v61, v2
	v_mov_b32_e32 v62, v2
	v_mov_b32_e32 v63, v2
	v_mov_b32_e32 v64, v2
	v_mov_b32_e32 v65, v2
	v_mov_b32_e32 v66, v2
	v_mov_b32_e32 v67, v2
	v_mov_b32_e32 v68, v2
	v_mov_b32_e32 v69, v2
	v_mov_b32_e32 v70, v2
	v_mov_b32_e32 v71, v2
	v_mov_b32_e32 v72, v2
	v_mov_b32_e32 v73, v2
	v_mov_b32_e32 v82, v2
	v_mov_b32_e32 v83, v2
	v_mov_b32_e32 v84, v2
	v_mov_b32_e32 v85, v2
	v_mov_b32_e32 v86, v2
	v_mov_b32_e32 v87, v2
	v_mov_b32_e32 v88, v2
	v_mov_b32_e32 v89, v2
	v_mov_b32_e32 v98, v2
	v_mov_b32_e32 v99, v2
	v_mov_b32_e32 v100, v2
	v_mov_b32_e32 v101, v2
	v_mov_b32_e32 v102, v2
	v_mov_b32_e32 v103, v2
	v_mov_b32_e32 v104, v2
	v_mov_b32_e32 v105, v2
	v_mov_b32_e32 v114, v2
	v_mov_b32_e32 v115, v2
	v_mov_b32_e32 v116, v2
	v_mov_b32_e32 v117, v2
	v_mov_b32_e32 v118, v2
	v_mov_b32_e32 v119, v2
	v_mov_b32_e32 v120, v2
	v_mov_b32_e32 v121, v2
	v_mov_b32_e32 v74, v2
	v_mov_b32_e32 v75, v2
	v_mov_b32_e32 v76, v2
	v_mov_b32_e32 v77, v2
	v_mov_b32_e32 v78, v2
	v_mov_b32_e32 v79, v2
	v_mov_b32_e32 v80, v2
	v_mov_b32_e32 v81, v2
	v_mov_b32_e32 v90, v2
	v_mov_b32_e32 v91, v2
	v_mov_b32_e32 v92, v2
	v_mov_b32_e32 v93, v2
	v_mov_b32_e32 v94, v2
	v_mov_b32_e32 v95, v2
	v_mov_b32_e32 v96, v2
	v_mov_b32_e32 v97, v2
	v_mov_b32_e32 v106, v2
	v_mov_b32_e32 v107, v2
	v_mov_b32_e32 v108, v2
	v_mov_b32_e32 v109, v2
	v_mov_b32_e32 v110, v2
	v_mov_b32_e32 v111, v2
	v_mov_b32_e32 v112, v2
	v_mov_b32_e32 v113, v2
	v_mov_b32_e32 v122, v2
	v_mov_b32_e32 v123, v2
	v_mov_b32_e32 v124, v2
	v_mov_b32_e32 v125, v2
	v_mov_b32_e32 v126, v2
	v_mov_b32_e32 v127, v2
	v_mov_b32_e32 v128, v2
	v_mov_b32_e32 v129, v2
	s_waitcnt vmcnt(0)
